# v_combo12 + GEMM accumulators cleared two registers at a time (v_pk_mov_b32 0,0)
# speedup vs baseline: 1.0016x; 1.0016x over previous
.LBB0_235:
	s_ashr_i32 s21, s20, 31
	s_lshl_b64 s[22:23], s[20:21], 19
	s_add_u32 s22, s33, s22
	s_addc_u32 s23, s40, s23
	s_and_b64 s[24:25], s[0:1], exec
	s_cselect_b32 s21, s23, s35
	s_cselect_b32 s62, s22, s34
	s_ashr_i32 s19, s18, 31
	s_lshl_b64 s[24:25], s[18:19], 19
	s_add_u32 s24, s41, s24
	s_addc_u32 s25, s42, s25
	s_and_b64 s[38:39], s[0:1], exec
	s_cselect_b32 s19, s25, s37
	s_cselect_b32 s63, s24, s36
	s_add_u32 s34, s34, 0x40080
	s_addc_u32 s35, s35, 0
	s_add_u32 s64, s36, 0x100
	v_mov_b32_e32 v0, 0
	s_addc_u32 s65, s37, 0
	s_mov_b32 s66, -2
	v_mov_b32_e32 v1, v0
	v_pk_mov_b32 v[2:3], 0, 0
	v_pk_mov_b32 v[4:5], 0, 0
	v_pk_mov_b32 v[6:7], 0, 0
	v_pk_mov_b32 v[8:9], 0, 0
	v_pk_mov_b32 v[10:11], 0, 0
	v_pk_mov_b32 v[16:17], 0, 0
	v_pk_mov_b32 v[18:19], 0, 0
	v_pk_mov_b32 v[24:25], 0, 0
	v_pk_mov_b32 v[26:27], 0, 0
	v_pk_mov_b32 v[32:33], 0, 0
	v_pk_mov_b32 v[34:35], 0, 0
	v_pk_mov_b32 v[40:41], 0, 0
	v_pk_mov_b32 v[42:43], 0, 0
	v_pk_mov_b32 v[48:49], 0, 0
	v_pk_mov_b32 v[50:51], 0, 0
	v_pk_mov_b32 v[12:13], 0, 0
	v_pk_mov_b32 v[14:15], 0, 0
	v_pk_mov_b32 v[20:21], 0, 0
	v_pk_mov_b32 v[22:23], 0, 0
	v_pk_mov_b32 v[28:29], 0, 0
	v_pk_mov_b32 v[30:31], 0, 0
	v_pk_mov_b32 v[36:37], 0, 0
	v_pk_mov_b32 v[38:39], 0, 0
	v_pk_mov_b32 v[44:45], 0, 0
	v_pk_mov_b32 v[46:47], 0, 0
	v_pk_mov_b32 v[52:53], 0, 0
	v_pk_mov_b32 v[54:55], 0, 0
	v_pk_mov_b32 v[56:57], 0, 0
	v_pk_mov_b32 v[58:59], 0, 0
	v_pk_mov_b32 v[60:61], 0, 0
	v_pk_mov_b32 v[62:63], 0, 0
	v_pk_mov_b32 v[64:65], 0, 0
	v_pk_mov_b32 v[66:67], 0, 0
	v_pk_mov_b32 v[68:69], 0, 0
	v_pk_mov_b32 v[70:71], 0, 0
	v_pk_mov_b32 v[80:81], 0, 0
	v_pk_mov_b32 v[82:83], 0, 0
	v_pk_mov_b32 v[84:85], 0, 0
	v_pk_mov_b32 v[86:87], 0, 0
	v_pk_mov_b32 v[88:89], 0, 0
	v_pk_mov_b32 v[90:91], 0, 0
	v_pk_mov_b32 v[92:93], 0, 0
	v_pk_mov_b32 v[94:95], 0, 0
	v_pk_mov_b32 v[96:97], 0, 0
	v_pk_mov_b32 v[98:99], 0, 0
	v_pk_mov_b32 v[104:105], 0, 0
	v_pk_mov_b32 v[106:107], 0, 0
	v_pk_mov_b32 v[72:73], 0, 0
	v_pk_mov_b32 v[74:75], 0, 0
	v_pk_mov_b32 v[76:77], 0, 0
	v_pk_mov_b32 v[78:79], 0, 0
	v_pk_mov_b32 v[100:101], 0, 0
	v_pk_mov_b32 v[102:103], 0, 0
	v_pk_mov_b32 v[108:109], 0, 0
	v_pk_mov_b32 v[110:111], 0, 0
	v_pk_mov_b32 v[112:113], 0, 0
	v_pk_mov_b32 v[114:115], 0, 0
	v_pk_mov_b32 v[116:117], 0, 0
	v_pk_mov_b32 v[118:119], 0, 0
	v_pk_mov_b32 v[120:121], 0, 0
	v_pk_mov_b32 v[122:123], 0, 0
	v_pk_mov_b32 v[124:125], 0, 0
	v_pk_mov_b32 v[126:127], 0, 0

.LBB0_444:
	s_ashr_i32 s39, s38, 31
	s_lshl_b64 s[40:41], s[38:39], 19
	s_add_u32 s40, s23, s40
	s_addc_u32 s41, s54, s41
	s_and_b64 s[42:43], s[4:5], exec
	s_cselect_b32 s1, s41, s47
	s_cselect_b32 s39, s40, s46
	s_ashr_i32 s37, s36, 31
	s_lshl_b64 s[42:43], s[36:37], 19
	s_add_u32 s42, s55, s42
	s_addc_u32 s43, s56, s43
	s_and_b64 s[50:51], s[4:5], exec
	s_cselect_b32 s37, s43, s49
	s_cselect_b32 s52, s42, s48
	s_add_u32 s46, s46, 0x40080
	s_addc_u32 s47, s47, 0
	s_add_u32 s53, s48, 0x100
	v_mov_b32_e32 v0, 0
	s_addc_u32 s72, s49, 0
	s_mov_b32 s73, -2
	v_mov_b32_e32 v1, v0
	v_pk_mov_b32 v[2:3], 0, 0
	v_pk_mov_b32 v[4:5], 0, 0
	v_pk_mov_b32 v[6:7], 0, 0
	v_pk_mov_b32 v[16:17], 0, 0
	v_pk_mov_b32 v[18:19], 0, 0
	v_pk_mov_b32 v[20:21], 0, 0
	v_pk_mov_b32 v[22:23], 0, 0
	v_pk_mov_b32 v[32:33], 0, 0
	v_pk_mov_b32 v[34:35], 0, 0
	v_pk_mov_b32 v[36:37], 0, 0
	v_pk_mov_b32 v[38:39], 0, 0
	v_pk_mov_b32 v[48:49], 0, 0
	v_pk_mov_b32 v[50:51], 0, 0
	v_pk_mov_b32 v[52:53], 0, 0
	v_pk_mov_b32 v[54:55], 0, 0
	v_pk_mov_b32 v[8:9], 0, 0
	v_pk_mov_b32 v[10:11], 0, 0
	v_pk_mov_b32 v[12:13], 0, 0
	v_pk_mov_b32 v[14:15], 0, 0
	v_pk_mov_b32 v[24:25], 0, 0
	v_pk_mov_b32 v[26:27], 0, 0
	v_pk_mov_b32 v[28:29], 0, 0
	v_pk_mov_b32 v[30:31], 0, 0
	v_pk_mov_b32 v[40:41], 0, 0
	v_pk_mov_b32 v[42:43], 0, 0
	v_pk_mov_b32 v[44:45], 0, 0
	v_pk_mov_b32 v[46:47], 0, 0
	v_pk_mov_b32 v[56:57], 0, 0
	v_pk_mov_b32 v[58:59], 0, 0
	v_pk_mov_b32 v[60:61], 0, 0
	v_pk_mov_b32 v[62:63], 0, 0
	v_pk_mov_b32 v[64:65], 0, 0
	v_pk_mov_b32 v[66:67], 0, 0
	v_pk_mov_b32 v[68:69], 0, 0
	v_pk_mov_b32 v[70:71], 0, 0
	v_pk_mov_b32 v[80:81], 0, 0
	v_pk_mov_b32 v[82:83], 0, 0
	v_pk_mov_b32 v[84:85], 0, 0
	v_pk_mov_b32 v[86:87], 0, 0
	v_pk_mov_b32 v[96:97], 0, 0
	v_pk_mov_b32 v[98:99], 0, 0
	v_pk_mov_b32 v[100:101], 0, 0
	v_pk_mov_b32 v[102:103], 0, 0
	v_pk_mov_b32 v[112:113], 0, 0
	v_pk_mov_b32 v[114:115], 0, 0
	v_pk_mov_b32 v[116:117], 0, 0
	v_pk_mov_b32 v[118:119], 0, 0
	v_pk_mov_b32 v[72:73], 0, 0
	v_pk_mov_b32 v[74:75], 0, 0
	v_pk_mov_b32 v[76:77], 0, 0
	v_pk_mov_b32 v[78:79], 0, 0
	v_pk_mov_b32 v[88:89], 0, 0
	v_pk_mov_b32 v[90:91], 0, 0
	v_pk_mov_b32 v[92:93], 0, 0
	v_pk_mov_b32 v[94:95], 0, 0
	v_pk_mov_b32 v[104:105], 0, 0
	v_pk_mov_b32 v[106:107], 0, 0
	v_pk_mov_b32 v[108:109], 0, 0
	v_pk_mov_b32 v[110:111], 0, 0
	v_pk_mov_b32 v[120:121], 0, 0
	v_pk_mov_b32 v[122:123], 0, 0
	v_pk_mov_b32 v[124:125], 0, 0
	v_pk_mov_b32 v[126:127], 0, 0

.LBB0_770:
	s_ashr_i32 s41, s40, 31
	s_lshl_b64 s[42:43], s[40:41], 19
	s_add_u32 s42, s23, s42
	s_addc_u32 s43, s52, s43
	s_and_b64 s[44:45], s[4:5], exec
	s_cselect_b32 s1, s43, s47
	s_cselect_b32 s7, s42, s46
	s_ashr_i32 s39, s38, 31
	s_lshl_b64 s[44:45], s[38:39], 19
	s_add_u32 s44, s53, s44
	s_addc_u32 s45, s54, s45
	s_and_b64 s[50:51], s[4:5], exec
	s_cselect_b32 s33, s45, s49
	s_cselect_b32 s39, s44, s48
	s_add_u32 s46, s46, 0x40080
	s_addc_u32 s47, s47, 0
	s_add_u32 s41, s48, 0x100
	v_mov_b32_e32 v0, 0
	s_addc_u32 s70, s49, 0
	s_mov_b32 s71, -2
	v_mov_b32_e32 v1, v0
	v_mov_b32_e32 v2, v0
	v_mov_b32_e32 v3, v0
	v_mov_b32_e32 v4, v0
	v_mov_b32_e32 v5, v0
	v_mov_b32_e32 v6, v0
	v_mov_b32_e32 v7, v0
	v_mov_b32_e32 v16, v0
	v_mov_b32_e32 v17, v0
	v_mov_b32_e32 v18, v0
	v_mov_b32_e32 v19, v0
	v_mov_b32_e32 v20, v0
	v_mov_b32_e32 v21, v0
	v_mov_b32_e32 v22, v0
	v_mov_b32_e32 v23, v0
	s_waitcnt vmcnt(0)
	v_pk_mov_b32 v[32:33], 0, 0
	v_pk_mov_b32 v[34:35], 0, 0
	v_pk_mov_b32 v[36:37], 0, 0
	v_pk_mov_b32 v[38:39], 0, 0
	v_pk_mov_b32 v[48:49], 0, 0
	v_pk_mov_b32 v[50:51], 0, 0
	v_pk_mov_b32 v[52:53], 0, 0
	v_pk_mov_b32 v[54:55], 0, 0
	v_pk_mov_b32 v[8:9], 0, 0
	v_pk_mov_b32 v[10:11], 0, 0
	v_pk_mov_b32 v[12:13], 0, 0
	v_pk_mov_b32 v[14:15], 0, 0
	v_pk_mov_b32 v[24:25], 0, 0
	v_pk_mov_b32 v[26:27], 0, 0
	v_pk_mov_b32 v[28:29], 0, 0
	v_pk_mov_b32 v[30:31], 0, 0
	v_pk_mov_b32 v[40:41], 0, 0
	v_pk_mov_b32 v[42:43], 0, 0
	v_pk_mov_b32 v[44:45], 0, 0
	v_pk_mov_b32 v[46:47], 0, 0
	v_pk_mov_b32 v[56:57], 0, 0
	v_pk_mov_b32 v[58:59], 0, 0
	v_pk_mov_b32 v[60:61], 0, 0
	v_pk_mov_b32 v[62:63], 0, 0
	v_pk_mov_b32 v[64:65], 0, 0
	v_pk_mov_b32 v[66:67], 0, 0
	v_pk_mov_b32 v[68:69], 0, 0
	v_pk_mov_b32 v[70:71], 0, 0
	v_pk_mov_b32 v[80:81], 0, 0
	v_pk_mov_b32 v[82:83], 0, 0
	v_pk_mov_b32 v[84:85], 0, 0
	v_pk_mov_b32 v[86:87], 0, 0
	v_pk_mov_b32 v[96:97], 0, 0
	v_pk_mov_b32 v[98:99], 0, 0
	v_pk_mov_b32 v[100:101], 0, 0
	v_pk_mov_b32 v[102:103], 0, 0
	v_pk_mov_b32 v[112:113], 0, 0
	v_pk_mov_b32 v[114:115], 0, 0
	v_pk_mov_b32 v[116:117], 0, 0
	v_pk_mov_b32 v[118:119], 0, 0
	v_pk_mov_b32 v[72:73], 0, 0
	v_pk_mov_b32 v[74:75], 0, 0
	v_pk_mov_b32 v[76:77], 0, 0
	v_pk_mov_b32 v[78:79], 0, 0
	v_pk_mov_b32 v[88:89], 0, 0
	v_pk_mov_b32 v[90:91], 0, 0
	v_pk_mov_b32 v[92:93], 0, 0
	v_pk_mov_b32 v[94:95], 0, 0
	v_pk_mov_b32 v[104:105], 0, 0
	v_pk_mov_b32 v[106:107], 0, 0
	v_pk_mov_b32 v[108:109], 0, 0
	v_pk_mov_b32 v[110:111], 0, 0
	v_pk_mov_b32 v[120:121], 0, 0
	v_pk_mov_b32 v[122:123], 0, 0
	v_pk_mov_b32 v[124:125], 0, 0
	v_pk_mov_b32 v[126:127], 0, 0

.LBB0_1032:
	s_ashr_i32 s35, s34, 31
	s_lshl_b64 s[36:37], s[34:35], 19
	s_add_u32 s36, s58, s36
	s_addc_u32 s37, s59, s37
	s_and_b64 s[38:39], s[6:7], exec
	s_cselect_b32 s1, s37, s41
	s_cselect_b32 s35, s36, s40
	s_ashr_i32 s27, s26, 31
	s_lshl_b64 s[38:39], s[26:27], 19
	s_add_u32 s38, s33, s38
	s_addc_u32 s39, s46, s39
	s_and_b64 s[44:45], s[6:7], exec
	s_cselect_b32 s27, s39, s43
	s_cselect_b32 s62, s38, s42
	s_add_u32 s40, s40, 0x40080
	s_addc_u32 s41, s41, 0
	s_add_u32 s63, s42, 0x100
	v_mov_b32_e32 v0, 0
	s_addc_u32 s64, s43, 0
	s_mov_b32 s65, -2
	v_mov_b32_e32 v1, v0
	v_mov_b32_e32 v2, v0
	v_mov_b32_e32 v3, v0
	v_mov_b32_e32 v4, v0
	v_mov_b32_e32 v5, v0
	v_mov_b32_e32 v6, v0
	v_mov_b32_e32 v7, v0
	s_waitcnt vmcnt(0)
	v_pk_mov_b32 v[16:17], 0, 0
	v_pk_mov_b32 v[18:19], 0, 0
	v_pk_mov_b32 v[20:21], 0, 0
	v_pk_mov_b32 v[22:23], 0, 0
	v_pk_mov_b32 v[32:33], 0, 0
	v_pk_mov_b32 v[34:35], 0, 0
	v_pk_mov_b32 v[36:37], 0, 0
	v_pk_mov_b32 v[38:39], 0, 0
	v_pk_mov_b32 v[48:49], 0, 0
	v_pk_mov_b32 v[50:51], 0, 0
	v_pk_mov_b32 v[52:53], 0, 0
	v_pk_mov_b32 v[54:55], 0, 0
	v_pk_mov_b32 v[8:9], 0, 0
	v_pk_mov_b32 v[10:11], 0, 0
	v_pk_mov_b32 v[12:13], 0, 0
	v_pk_mov_b32 v[14:15], 0, 0
	v_pk_mov_b32 v[24:25], 0, 0
	v_pk_mov_b32 v[26:27], 0, 0
	v_pk_mov_b32 v[28:29], 0, 0
	v_pk_mov_b32 v[30:31], 0, 0
	v_pk_mov_b32 v[40:41], 0, 0
	v_pk_mov_b32 v[42:43], 0, 0
	v_pk_mov_b32 v[44:45], 0, 0
	v_pk_mov_b32 v[46:47], 0, 0
	v_pk_mov_b32 v[56:57], 0, 0
	v_pk_mov_b32 v[58:59], 0, 0
	v_pk_mov_b32 v[60:61], 0, 0
	v_pk_mov_b32 v[62:63], 0, 0
	v_pk_mov_b32 v[64:65], 0, 0
	v_pk_mov_b32 v[66:67], 0, 0
	v_pk_mov_b32 v[68:69], 0, 0
	v_pk_mov_b32 v[70:71], 0, 0
	v_pk_mov_b32 v[80:81], 0, 0
	v_pk_mov_b32 v[82:83], 0, 0
	v_pk_mov_b32 v[84:85], 0, 0
	v_pk_mov_b32 v[86:87], 0, 0
	v_pk_mov_b32 v[96:97], 0, 0
	v_pk_mov_b32 v[98:99], 0, 0
	v_pk_mov_b32 v[100:101], 0, 0
	v_pk_mov_b32 v[102:103], 0, 0
	v_pk_mov_b32 v[112:113], 0, 0
	v_pk_mov_b32 v[114:115], 0, 0
	v_pk_mov_b32 v[116:117], 0, 0
	v_pk_mov_b32 v[118:119], 0, 0
	v_pk_mov_b32 v[72:73], 0, 0
	v_pk_mov_b32 v[74:75], 0, 0
	v_pk_mov_b32 v[76:77], 0, 0
	v_pk_mov_b32 v[78:79], 0, 0
	v_pk_mov_b32 v[88:89], 0, 0
	v_pk_mov_b32 v[90:91], 0, 0
	v_pk_mov_b32 v[92:93], 0, 0
	v_pk_mov_b32 v[94:95], 0, 0
	v_pk_mov_b32 v[104:105], 0, 0
	v_pk_mov_b32 v[106:107], 0, 0
	v_pk_mov_b32 v[108:109], 0, 0
	v_pk_mov_b32 v[110:111], 0, 0
	v_pk_mov_b32 v[120:121], 0, 0
	v_pk_mov_b32 v[122:123], 0, 0
	v_pk_mov_b32 v[124:125], 0, 0
	v_pk_mov_b32 v[126:127], 0, 0

.LBB0_1090:
	s_ashr_i32 s39, s38, 31
	s_lshl_b64 s[40:41], s[38:39], 19
	s_add_u32 s40, s51, s40
	s_addc_u32 s41, s52, s41
	s_and_b64 s[42:43], s[6:7], exec
	s_cselect_b32 s1, s41, s45
	s_cselect_b32 s33, s40, s44
	s_ashr_i32 s37, s36, 31
	s_lshl_b64 s[42:43], s[36:37], 19
	s_add_u32 s42, s53, s42
	s_addc_u32 s43, s54, s43
	s_and_b64 s[48:49], s[6:7], exec
	s_cselect_b32 s37, s43, s47
	s_cselect_b32 s39, s42, s46
	s_add_u32 s44, s44, 0x40080
	s_addc_u32 s45, s45, 0
	s_add_u32 s69, s46, 0x100
	v_mov_b32_e32 v0, 0
	s_addc_u32 s70, s47, 0
	s_mov_b32 s71, -2
	v_mov_b32_e32 v1, v0
	v_pk_mov_b32 v[2:3], 0, 0
	v_pk_mov_b32 v[4:5], 0, 0
	v_pk_mov_b32 v[6:7], 0, 0
	v_pk_mov_b32 v[16:17], 0, 0
	v_pk_mov_b32 v[18:19], 0, 0
	v_pk_mov_b32 v[20:21], 0, 0
	v_pk_mov_b32 v[22:23], 0, 0
	v_pk_mov_b32 v[32:33], 0, 0
	v_pk_mov_b32 v[34:35], 0, 0
	v_pk_mov_b32 v[36:37], 0, 0
	v_pk_mov_b32 v[38:39], 0, 0
	v_pk_mov_b32 v[48:49], 0, 0
	v_pk_mov_b32 v[50:51], 0, 0
	v_pk_mov_b32 v[52:53], 0, 0
	v_pk_mov_b32 v[54:55], 0, 0
	v_pk_mov_b32 v[8:9], 0, 0
	v_pk_mov_b32 v[10:11], 0, 0
	v_pk_mov_b32 v[12:13], 0, 0
	v_pk_mov_b32 v[14:15], 0, 0
	v_pk_mov_b32 v[24:25], 0, 0
	v_pk_mov_b32 v[26:27], 0, 0
	v_pk_mov_b32 v[28:29], 0, 0
	v_pk_mov_b32 v[30:31], 0, 0
	v_pk_mov_b32 v[40:41], 0, 0
	v_pk_mov_b32 v[42:43], 0, 0
	v_pk_mov_b32 v[44:45], 0, 0
	v_pk_mov_b32 v[46:47], 0, 0
	v_pk_mov_b32 v[56:57], 0, 0
	v_pk_mov_b32 v[58:59], 0, 0
	v_pk_mov_b32 v[60:61], 0, 0
	v_pk_mov_b32 v[62:63], 0, 0
	v_pk_mov_b32 v[64:65], 0, 0
	v_pk_mov_b32 v[66:67], 0, 0
	v_pk_mov_b32 v[68:69], 0, 0
	v_pk_mov_b32 v[70:71], 0, 0
	v_pk_mov_b32 v[80:81], 0, 0
	v_pk_mov_b32 v[82:83], 0, 0
	v_pk_mov_b32 v[84:85], 0, 0
	v_pk_mov_b32 v[86:87], 0, 0
	v_pk_mov_b32 v[96:97], 0, 0
	v_pk_mov_b32 v[98:99], 0, 0
	v_pk_mov_b32 v[100:101], 0, 0
	v_pk_mov_b32 v[102:103], 0, 0
	v_pk_mov_b32 v[112:113], 0, 0
	v_pk_mov_b32 v[114:115], 0, 0
	v_pk_mov_b32 v[116:117], 0, 0
	v_pk_mov_b32 v[118:119], 0, 0
	v_pk_mov_b32 v[72:73], 0, 0
	v_pk_mov_b32 v[74:75], 0, 0
	v_pk_mov_b32 v[76:77], 0, 0
	v_pk_mov_b32 v[78:79], 0, 0
	v_pk_mov_b32 v[88:89], 0, 0
	v_pk_mov_b32 v[90:91], 0, 0
	v_pk_mov_b32 v[92:93], 0, 0
	v_pk_mov_b32 v[94:95], 0, 0
	v_pk_mov_b32 v[104:105], 0, 0
	v_pk_mov_b32 v[106:107], 0, 0
	v_pk_mov_b32 v[108:109], 0, 0
	v_pk_mov_b32 v[110:111], 0, 0
	v_pk_mov_b32 v[120:121], 0, 0
	v_pk_mov_b32 v[122:123], 0, 0
	v_pk_mov_b32 v[124:125], 0, 0
	v_pk_mov_b32 v[126:127], 0, 0

.LBB0_1182:
	s_ashr_i32 s45, s44, 31
	s_lshl_b64 s[46:47], s[44:45], 19
	s_add_u32 s46, s10, s46
	s_addc_u32 s47, s11, s47
	s_and_b64 s[48:49], s[0:1], exec
	s_cselect_b32 s45, s47, s53
	s_cselect_b32 s73, s46, s52
	s_ashr_i32 s43, s42, 31
	s_lshl_b64 s[48:49], s[42:43], 19
	s_add_u32 s48, s33, s48
	s_addc_u32 s49, s60, s49
	s_and_b64 s[56:57], s[0:1], exec
	s_cselect_b32 s43, s49, s55
	s_cselect_b32 s74, s48, s54
	s_add_u32 s52, s52, 0x40080
	s_addc_u32 s53, s53, 0
	s_add_u32 s75, s54, 0x100
	v_mov_b32_e32 v0, 0
	s_addc_u32 s76, s55, 0
	s_mov_b32 s77, -2
	v_mov_b32_e32 v1, v0
	v_pk_mov_b32 v[2:3], 0, 0
	v_pk_mov_b32 v[4:5], 0, 0
	v_pk_mov_b32 v[6:7], 0, 0
	v_pk_mov_b32 v[16:17], 0, 0
	v_pk_mov_b32 v[18:19], 0, 0
	v_pk_mov_b32 v[20:21], 0, 0
	v_pk_mov_b32 v[22:23], 0, 0
	v_pk_mov_b32 v[32:33], 0, 0
	v_pk_mov_b32 v[34:35], 0, 0
	v_pk_mov_b32 v[36:37], 0, 0
	v_pk_mov_b32 v[38:39], 0, 0
	v_pk_mov_b32 v[48:49], 0, 0
	v_pk_mov_b32 v[50:51], 0, 0
	v_pk_mov_b32 v[52:53], 0, 0
	v_pk_mov_b32 v[54:55], 0, 0
	v_pk_mov_b32 v[8:9], 0, 0
	v_pk_mov_b32 v[10:11], 0, 0
	v_pk_mov_b32 v[12:13], 0, 0
	v_pk_mov_b32 v[14:15], 0, 0
	v_pk_mov_b32 v[24:25], 0, 0
	v_pk_mov_b32 v[26:27], 0, 0
	v_pk_mov_b32 v[28:29], 0, 0
	v_pk_mov_b32 v[30:31], 0, 0
	v_pk_mov_b32 v[40:41], 0, 0
	v_pk_mov_b32 v[42:43], 0, 0
	v_pk_mov_b32 v[44:45], 0, 0
	v_pk_mov_b32 v[46:47], 0, 0
	v_pk_mov_b32 v[56:57], 0, 0
	v_pk_mov_b32 v[58:59], 0, 0
	v_pk_mov_b32 v[60:61], 0, 0
	v_pk_mov_b32 v[62:63], 0, 0
	v_pk_mov_b32 v[64:65], 0, 0
	v_pk_mov_b32 v[66:67], 0, 0
	v_pk_mov_b32 v[68:69], 0, 0
	v_pk_mov_b32 v[70:71], 0, 0
	v_pk_mov_b32 v[80:81], 0, 0
	v_pk_mov_b32 v[82:83], 0, 0
	v_pk_mov_b32 v[84:85], 0, 0
	v_pk_mov_b32 v[86:87], 0, 0
	v_pk_mov_b32 v[96:97], 0, 0
	v_pk_mov_b32 v[98:99], 0, 0
	v_pk_mov_b32 v[100:101], 0, 0
	v_pk_mov_b32 v[102:103], 0, 0
	v_pk_mov_b32 v[112:113], 0, 0
	v_pk_mov_b32 v[114:115], 0, 0
	v_pk_mov_b32 v[116:117], 0, 0
	v_pk_mov_b32 v[118:119], 0, 0
	v_pk_mov_b32 v[72:73], 0, 0
	v_pk_mov_b32 v[74:75], 0, 0
	v_pk_mov_b32 v[76:77], 0, 0
	v_pk_mov_b32 v[78:79], 0, 0
	v_pk_mov_b32 v[88:89], 0, 0
	v_pk_mov_b32 v[90:91], 0, 0
	v_pk_mov_b32 v[92:93], 0, 0
	v_pk_mov_b32 v[94:95], 0, 0
	v_pk_mov_b32 v[104:105], 0, 0
	v_pk_mov_b32 v[106:107], 0, 0
	v_pk_mov_b32 v[108:109], 0, 0
	v_pk_mov_b32 v[110:111], 0, 0
	v_pk_mov_b32 v[120:121], 0, 0
	v_pk_mov_b32 v[122:123], 0, 0
	v_pk_mov_b32 v[124:125], 0, 0
	v_pk_mov_b32 v[126:127], 0, 0

.LBB0_1268:
	s_ashr_i32 s25, s24, 31
	s_lshl_b64 s[26:27], s[24:25], 19
	s_add_u32 s26, s2, s26
	s_addc_u32 s27, s3, s27
	s_and_b64 s[34:35], s[0:1], exec
	s_cselect_b32 s25, s27, s39
	s_cselect_b32 s37, s26, s38
	s_ashr_i32 s23, s22, 31
	s_lshl_b64 s[34:35], s[22:23], 19
	s_add_u32 s34, s44, s34
	s_addc_u32 s35, s45, s35
	s_and_b64 s[42:43], s[0:1], exec
	s_cselect_b32 s23, s35, s41
	s_cselect_b32 s66, s34, s40
	s_add_u32 s38, s38, 0x40080
	s_addc_u32 s39, s39, 0
	s_add_u32 s67, s40, 0x100
	v_mov_b32_e32 v0, 0
	s_addc_u32 s68, s41, 0
	s_mov_b32 s69, -2
	v_mov_b32_e32 v1, v0
	v_pk_mov_b32 v[2:3], 0, 0
	v_pk_mov_b32 v[4:5], 0, 0
	v_pk_mov_b32 v[6:7], 0, 0
	v_pk_mov_b32 v[8:9], 0, 0
	v_pk_mov_b32 v[10:11], 0, 0
	v_pk_mov_b32 v[16:17], 0, 0
	v_pk_mov_b32 v[18:19], 0, 0
	v_pk_mov_b32 v[24:25], 0, 0
	v_pk_mov_b32 v[26:27], 0, 0
	v_pk_mov_b32 v[32:33], 0, 0
	v_pk_mov_b32 v[34:35], 0, 0
	v_pk_mov_b32 v[40:41], 0, 0
	v_pk_mov_b32 v[42:43], 0, 0
	v_pk_mov_b32 v[48:49], 0, 0
	v_pk_mov_b32 v[50:51], 0, 0
	v_pk_mov_b32 v[12:13], 0, 0
	v_pk_mov_b32 v[14:15], 0, 0
	v_pk_mov_b32 v[20:21], 0, 0
	v_pk_mov_b32 v[22:23], 0, 0
	v_pk_mov_b32 v[28:29], 0, 0
	v_pk_mov_b32 v[30:31], 0, 0
	v_pk_mov_b32 v[36:37], 0, 0
	v_pk_mov_b32 v[38:39], 0, 0
	v_pk_mov_b32 v[44:45], 0, 0
	v_pk_mov_b32 v[46:47], 0, 0
	v_pk_mov_b32 v[52:53], 0, 0
	v_pk_mov_b32 v[54:55], 0, 0
	v_pk_mov_b32 v[56:57], 0, 0
	v_pk_mov_b32 v[58:59], 0, 0
	v_pk_mov_b32 v[60:61], 0, 0
	v_pk_mov_b32 v[62:63], 0, 0
	v_pk_mov_b32 v[64:65], 0, 0
	v_pk_mov_b32 v[66:67], 0, 0
	v_pk_mov_b32 v[68:69], 0, 0
	v_pk_mov_b32 v[70:71], 0, 0
	v_pk_mov_b32 v[80:81], 0, 0
	v_pk_mov_b32 v[82:83], 0, 0
	v_pk_mov_b32 v[84:85], 0, 0
	v_pk_mov_b32 v[86:87], 0, 0
	v_pk_mov_b32 v[88:89], 0, 0
	v_pk_mov_b32 v[90:91], 0, 0
	v_pk_mov_b32 v[92:93], 0, 0
	v_pk_mov_b32 v[94:95], 0, 0
	v_pk_mov_b32 v[96:97], 0, 0
	v_pk_mov_b32 v[98:99], 0, 0
	v_pk_mov_b32 v[104:105], 0, 0
	v_pk_mov_b32 v[106:107], 0, 0
	v_pk_mov_b32 v[72:73], 0, 0
	v_pk_mov_b32 v[74:75], 0, 0
	v_pk_mov_b32 v[76:77], 0, 0
	v_pk_mov_b32 v[78:79], 0, 0
	v_pk_mov_b32 v[100:101], 0, 0
	v_pk_mov_b32 v[102:103], 0, 0
	v_pk_mov_b32 v[108:109], 0, 0
	v_pk_mov_b32 v[110:111], 0, 0
	v_pk_mov_b32 v[112:113], 0, 0
	v_pk_mov_b32 v[114:115], 0, 0
	v_pk_mov_b32 v[116:117], 0, 0
	v_pk_mov_b32 v[118:119], 0, 0
	v_pk_mov_b32 v[120:121], 0, 0
	v_pk_mov_b32 v[122:123], 0, 0
	v_pk_mov_b32 v[124:125], 0, 0
	v_pk_mov_b32 v[126:127], 0, 0
